# adaLN silu(cond) staging: 18 serialized load+wait iterations replaced by 18 loads issued ahead of the weight loads, one counted wait, unrolled compute
# speedup vs baseline: 1.0120x; 1.0120x over previous
.LBB0_55:
	v_and_b32_e32 v109, 31, v2
	v_lshl_or_b32 v8, s3, 5, v109
	s_mov_b32 s27, 0x2aaaaaab
	v_mul_hi_i32 v1, v8, s27
	v_lshrrev_b32_e32 v3, 31, v1
	v_ashrrev_i32_e32 v1, 9, v1
	v_add_u32_e32 v15, v1, v3
	s_waitcnt lgkmcnt(0)
	v_lshlrev_b32_e32 v112, 2, v0
	v_mov_b32_e32 v113, 0
	s_mov_b64 s[98:99], 0x1000
	v_lshl_add_u64 v[114:115], s[36:37], 0, v[112:113]
	v_lshl_add_u64 v[112:113], s[34:35], 0, v[112:113]
	global_load_dword v126, v[114:115], off
	global_load_dword v127, v[114:115], off offset:2048
	v_lshl_add_u64 v[114:115], v[114:115], 0, s[98:99]
	global_load_dword v128, v[114:115], off
	global_load_dword v129, v[114:115], off offset:2048
	v_lshl_add_u64 v[114:115], v[114:115], 0, s[98:99]
	global_load_dword v130, v[114:115], off
	global_load_dword v131, v[114:115], off offset:2048
	v_lshl_add_u64 v[114:115], v[114:115], 0, s[98:99]
	global_load_dword v132, v[114:115], off
	global_load_dword v133, v[114:115], off offset:2048
	v_lshl_add_u64 v[114:115], v[114:115], 0, s[98:99]
	global_load_dword v134, v[114:115], off
	global_load_dword v135, v[114:115], off offset:2048
	v_lshl_add_u64 v[114:115], v[114:115], 0, s[98:99]
	global_load_dword v136, v[114:115], off
	global_load_dword v137, v[114:115], off offset:2048
	v_lshl_add_u64 v[114:115], v[114:115], 0, s[98:99]
	global_load_dword v138, v[114:115], off
	global_load_dword v139, v[114:115], off offset:2048
	v_lshl_add_u64 v[114:115], v[114:115], 0, s[98:99]
	global_load_dword v140, v[114:115], off
	global_load_dword v141, v[114:115], off offset:2048
	global_load_dword v142, v[112:113], off
	global_load_dword v143, v[112:113], off offset:2048
	v_mov_b64_e32 v[4:5], s[40:41]
	s_and_b64 s[40:41], s[4:5], exec
	v_mul_i32_i24_e32 v1, 0xc00, v15
	s_mov_b32 s27, 0xc00000
	s_cselect_b32 s31, s15, s31
	s_cselect_b32 s39, s14, s30
	s_ashr_i32 s43, s42, 31
	v_sub_u32_e32 v6, v8, v1
	v_mad_i64_i32 v[4:5], s[40:41], v15, s27, v[4:5]
	s_lshl_b32 s30, s26, 6
	s_lshl_b64 s[26:27], s[42:43], 2
	v_ashrrev_i32_e32 v7, 31, v6
	v_ashrrev_i32_e32 v3, 5, v2
	s_add_u32 s26, s39, s26
	v_mov_b32_e32 v11, 0
	v_lshl_add_u64 v[12:13], v[6:7], 2, v[4:5]
	v_add_u32_e32 v1, s30, v3
	s_addc_u32 s27, s31, s27
	v_lshlrev_b32_e32 v4, 2, v109
	v_mov_b32_e32 v5, v11
	v_lshl_add_u64 v[38:39], s[26:27], 0, v[4:5]
	v_mad_i64_i32 v[16:17], s[26:27], s38, v1, 0
	v_add_u32_e32 v5, 2, v1
	v_lshl_add_u64 v[22:23], v[16:17], 2, v[38:39]
	v_mad_i64_i32 v[16:17], s[26:27], s38, v5, 0
	v_add_u32_e32 v5, 4, v1
	v_lshl_add_u64 v[24:25], v[16:17], 2, v[38:39]
	v_mad_i64_i32 v[16:17], s[26:27], s38, v5, 0
	v_add_u32_e32 v5, 6, v1
	v_lshl_add_u64 v[26:27], v[16:17], 2, v[38:39]
	v_mad_i64_i32 v[16:17], s[26:27], s38, v5, 0
	v_add_u32_e32 v5, 8, v1
	v_lshl_add_u64 v[28:29], v[16:17], 2, v[38:39]
	v_mad_i64_i32 v[16:17], s[26:27], s38, v5, 0
	v_add_u32_e32 v5, 10, v1
	v_lshl_add_u64 v[30:31], v[16:17], 2, v[38:39]
	v_mad_i64_i32 v[16:17], s[26:27], s38, v5, 0
	v_add_u32_e32 v5, 12, v1
	v_lshl_add_u64 v[32:33], v[16:17], 2, v[38:39]
	v_mad_i64_i32 v[16:17], s[26:27], s38, v5, 0
	v_add_u32_e32 v5, 14, v1
	v_lshl_add_u64 v[34:35], v[16:17], 2, v[38:39]
	v_mad_i64_i32 v[16:17], s[26:27], s38, v5, 0
	v_add_u32_e32 v9, 16, v1
	v_lshl_add_u64 v[36:37], v[16:17], 2, v[38:39]
	global_load_dword v5, v[22:23], off nt
	global_load_dword v7, v[24:25], off nt
	global_load_dword v16, v[26:27], off nt
	global_load_dword v18, v[28:29], off nt
	global_load_dword v17, v[30:31], off nt
	global_load_dword v19, v[32:33], off nt
	global_load_dword v20, v[34:35], off nt
	global_load_dword v21, v[36:37], off nt
	v_mad_i64_i32 v[22:23], s[26:27], s38, v9, 0
	v_add_u32_e32 v9, 18, v1
	v_lshl_add_u64 v[30:31], v[22:23], 2, v[38:39]
	v_mad_i64_i32 v[22:23], s[26:27], s38, v9, 0
	v_add_u32_e32 v9, 20, v1
	v_lshl_add_u64 v[32:33], v[22:23], 2, v[38:39]
	v_mad_i64_i32 v[22:23], s[26:27], s38, v9, 0
	v_add_u32_e32 v9, 22, v1
	v_lshl_add_u64 v[34:35], v[22:23], 2, v[38:39]
	v_mad_i64_i32 v[22:23], s[26:27], s38, v9, 0
	v_add_u32_e32 v9, 24, v1
	v_lshl_add_u64 v[36:37], v[22:23], 2, v[38:39]
	v_mad_i64_i32 v[22:23], s[26:27], s38, v9, 0
	v_add_u32_e32 v9, 26, v1
	v_lshl_add_u64 v[40:41], v[22:23], 2, v[38:39]
	v_mad_i64_i32 v[22:23], s[26:27], s38, v9, 0
	v_add_u32_e32 v9, 28, v1
	v_lshl_add_u64 v[42:43], v[22:23], 2, v[38:39]
	v_mad_i64_i32 v[22:23], s[26:27], s38, v9, 0
	v_add_u32_e32 v9, 30, v1
	v_lshl_add_u64 v[44:45], v[22:23], 2, v[38:39]
	v_mad_i64_i32 v[22:23], s[26:27], s38, v9, 0
	v_add_u32_e32 v9, 32, v1
	v_lshl_add_u64 v[46:47], v[22:23], 2, v[38:39]
	global_load_dword v22, v[30:31], off nt
	global_load_dword v23, v[32:33], off nt
	global_load_dword v24, v[34:35], off nt
	global_load_dword v26, v[36:37], off nt
	global_load_dword v25, v[40:41], off nt
	global_load_dword v27, v[42:43], off nt
	global_load_dword v28, v[44:45], off nt
	global_load_dword v29, v[46:47], off nt
	v_mad_i64_i32 v[30:31], s[26:27], s38, v9, 0
	v_add_u32_e32 v9, 34, v1
	v_lshl_add_u64 v[40:41], v[30:31], 2, v[38:39]
	v_mad_i64_i32 v[30:31], s[26:27], s38, v9, 0
	v_add_u32_e32 v9, 36, v1
	v_lshl_add_u64 v[42:43], v[30:31], 2, v[38:39]
	v_mad_i64_i32 v[30:31], s[26:27], s38, v9, 0
	v_add_u32_e32 v9, 38, v1
	v_lshl_add_u64 v[44:45], v[30:31], 2, v[38:39]
	v_mad_i64_i32 v[30:31], s[26:27], s38, v9, 0
	v_add_u32_e32 v9, 40, v1
	v_lshl_add_u64 v[46:47], v[30:31], 2, v[38:39]
	v_mad_i64_i32 v[30:31], s[26:27], s38, v9, 0
	v_add_u32_e32 v9, 42, v1
	v_lshl_add_u64 v[48:49], v[30:31], 2, v[38:39]
	v_mad_i64_i32 v[30:31], s[26:27], s38, v9, 0
	v_add_u32_e32 v9, 44, v1
	v_lshl_add_u64 v[50:51], v[30:31], 2, v[38:39]
	v_mad_i64_i32 v[30:31], s[26:27], s38, v9, 0
	v_add_u32_e32 v9, 46, v1
	v_lshl_add_u64 v[52:53], v[30:31], 2, v[38:39]
	v_mad_i64_i32 v[30:31], s[26:27], s38, v9, 0
	v_add_u32_e32 v9, 48, v1
	v_lshl_add_u64 v[54:55], v[30:31], 2, v[38:39]
	global_load_dword v30, v[40:41], off nt
	global_load_dword v31, v[42:43], off nt
	global_load_dword v32, v[44:45], off nt
	global_load_dword v34, v[46:47], off nt
	global_load_dword v33, v[48:49], off nt
	global_load_dword v35, v[50:51], off nt
	global_load_dword v36, v[52:53], off nt
	global_load_dword v37, v[54:55], off nt
	v_mad_i64_i32 v[40:41], s[26:27], s38, v9, 0
	v_add_u32_e32 v9, 50, v1
	v_lshl_add_u64 v[46:47], v[40:41], 2, v[38:39]
	v_mad_i64_i32 v[40:41], s[26:27], s38, v9, 0
	v_add_u32_e32 v9, 52, v1
	v_lshl_add_u64 v[48:49], v[40:41], 2, v[38:39]
	v_mad_i64_i32 v[40:41], s[26:27], s38, v9, 0
	v_add_u32_e32 v9, 54, v1
	v_lshl_add_u64 v[50:51], v[40:41], 2, v[38:39]
	v_mad_i64_i32 v[40:41], s[26:27], s38, v9, 0
	v_add_u32_e32 v9, 56, v1
	v_lshl_add_u64 v[52:53], v[40:41], 2, v[38:39]
	v_mad_i64_i32 v[40:41], s[26:27], s38, v9, 0
	v_add_u32_e32 v9, 58, v1
	v_lshl_add_u64 v[54:55], v[40:41], 2, v[38:39]
	v_mad_i64_i32 v[40:41], s[26:27], s38, v9, 0
	v_add_u32_e32 v9, 60, v1
	v_ashrrev_i32_e32 v14, 5, v0
	v_lshl_add_u64 v[56:57], v[40:41], 2, v[38:39]
	v_mad_i64_i32 v[40:41], s[26:27], s38, v9, 0
	v_add_u32_e32 v1, 62, v1
	v_lshl_add_u64 v[58:59], v[40:41], 2, v[38:39]
	v_mad_i64_i32 v[40:41], s[26:27], s38, v1, 0
	v_lshlrev_b32_e32 v1, 6, v14
	s_movk_i32 s26, 0x3000
	v_or_b32_e32 v9, 1, v1
	v_lshl_add_u64 v[60:61], v[40:41], 2, v[38:39]
	global_load_dword v38, v[46:47], off nt
	global_load_dword v39, v[48:49], off nt
	global_load_dword v40, v[50:51], off nt
	global_load_dword v42, v[52:53], off nt
	global_load_dword v41, v[54:55], off nt
	global_load_dword v43, v[56:57], off nt
	global_load_dword v44, v[58:59], off nt
	global_load_dword v45, v[60:61], off nt
	v_mad_i64_i32 v[56:57], s[38:39], v9, s26, v[12:13]
	v_or_b32_e32 v9, 2, v1
	v_mad_i64_i32 v[58:59], s[38:39], v9, s26, v[12:13]
	v_or_b32_e32 v9, 3, v1
	v_mad_i64_i32 v[60:61], s[38:39], v9, s26, v[12:13]
	v_or_b32_e32 v9, 4, v1
	v_mad_i64_i32 v[62:63], s[38:39], v9, s26, v[12:13]
	v_or_b32_e32 v9, 5, v1
	v_mad_i64_i32 v[64:65], s[38:39], v9, s26, v[12:13]
	v_or_b32_e32 v9, 6, v1
	v_mad_i64_i32 v[54:55], s[38:39], v1, s26, v[12:13]
	v_mad_i64_i32 v[66:67], s[38:39], v9, s26, v[12:13]
	v_or_b32_e32 v9, 7, v1
	v_or_b32_e32 v10, 8, v1
	v_mad_i64_i32 v[68:69], s[38:39], v9, s26, v[12:13]
	global_load_dword v50, v[54:55], off nt
	global_load_dword v52, v[56:57], off nt
	global_load_dword v51, v[58:59], off nt
	global_load_dword v48, v[60:61], off nt
	global_load_dword v46, v[62:63], off nt
	global_load_dword v49, v[64:65], off nt
	global_load_dword v47, v[66:67], off nt
	global_load_dword v9, v[68:69], off nt
	v_mad_i64_i32 v[62:63], s[38:39], v10, s26, v[12:13]
	v_or_b32_e32 v10, 9, v1
	v_mad_i64_i32 v[64:65], s[38:39], v10, s26, v[12:13]
	v_or_b32_e32 v10, 10, v1
	v_mad_i64_i32 v[66:67], s[38:39], v10, s26, v[12:13]
	v_or_b32_e32 v10, 11, v1
	v_mad_i64_i32 v[68:69], s[38:39], v10, s26, v[12:13]
	v_or_b32_e32 v10, 12, v1
	v_mad_i64_i32 v[70:71], s[38:39], v10, s26, v[12:13]
	v_or_b32_e32 v10, 13, v1
	v_mad_i64_i32 v[72:73], s[38:39], v10, s26, v[12:13]
	v_or_b32_e32 v10, 14, v1
	v_mad_i64_i32 v[74:75], s[38:39], v10, s26, v[12:13]
	v_or_b32_e32 v10, 15, v1
	v_mad_i64_i32 v[76:77], s[38:39], v10, s26, v[12:13]
	v_or_b32_e32 v10, 16, v1
	global_load_dword v58, v[62:63], off nt
	global_load_dword v60, v[64:65], off nt
	global_load_dword v59, v[66:67], off nt
	global_load_dword v56, v[68:69], off nt
	global_load_dword v55, v[70:71], off nt
	global_load_dword v57, v[72:73], off nt
	global_load_dword v53, v[74:75], off nt
	global_load_dword v54, v[76:77], off nt
	v_mad_i64_i32 v[70:71], s[38:39], v10, s26, v[12:13]
	v_or_b32_e32 v10, 17, v1
	v_mad_i64_i32 v[72:73], s[38:39], v10, s26, v[12:13]
	v_or_b32_e32 v10, 18, v1
	v_mad_i64_i32 v[74:75], s[38:39], v10, s26, v[12:13]
	v_or_b32_e32 v10, 19, v1
	v_mad_i64_i32 v[76:77], s[38:39], v10, s26, v[12:13]
	v_or_b32_e32 v10, 20, v1
	v_mad_i64_i32 v[78:79], s[38:39], v10, s26, v[12:13]
	v_or_b32_e32 v10, 21, v1
	v_mad_i64_i32 v[80:81], s[38:39], v10, s26, v[12:13]
	v_or_b32_e32 v10, 22, v1
	v_mad_i64_i32 v[82:83], s[38:39], v10, s26, v[12:13]
	v_or_b32_e32 v10, 23, v1
	v_mad_i64_i32 v[84:85], s[38:39], v10, s26, v[12:13]
	v_or_b32_e32 v10, 24, v1
	global_load_dword v64, v[70:71], off nt
	global_load_dword v68, v[72:73], off nt
	global_load_dword v65, v[74:75], off nt
	global_load_dword v66, v[76:77], off nt
	global_load_dword v63, v[78:79], off nt
	global_load_dword v67, v[80:81], off nt
	global_load_dword v61, v[82:83], off nt
	global_load_dword v62, v[84:85], off nt
	v_mad_i64_i32 v[78:79], s[38:39], v10, s26, v[12:13]
	v_or_b32_e32 v10, 25, v1
	v_mad_i64_i32 v[80:81], s[38:39], v10, s26, v[12:13]
	v_or_b32_e32 v10, 26, v1
	v_mad_i64_i32 v[82:83], s[38:39], v10, s26, v[12:13]
	v_or_b32_e32 v10, 27, v1
	v_mad_i64_i32 v[84:85], s[38:39], v10, s26, v[12:13]
	v_or_b32_e32 v10, 28, v1
	v_mad_i64_i32 v[86:87], s[38:39], v10, s26, v[12:13]
	v_or_b32_e32 v10, 29, v1
	v_mad_i64_i32 v[88:89], s[38:39], v10, s26, v[12:13]
	v_or_b32_e32 v10, 30, v1
	v_mad_i64_i32 v[90:91], s[38:39], v10, s26, v[12:13]
	v_or_b32_e32 v10, 31, v1
	v_mad_i64_i32 v[92:93], s[38:39], v10, s26, v[12:13]
	v_or_b32_e32 v10, 32, v1
	global_load_dword v72, v[78:79], off nt
	global_load_dword v76, v[80:81], off nt
	global_load_dword v73, v[82:83], off nt
	global_load_dword v74, v[84:85], off nt
	global_load_dword v71, v[86:87], off nt
	global_load_dword v75, v[88:89], off nt
	global_load_dword v69, v[90:91], off nt
	global_load_dword v70, v[92:93], off nt
	v_mad_i64_i32 v[86:87], s[38:39], v10, s26, v[12:13]
	v_or_b32_e32 v10, 33, v1
	v_mad_i64_i32 v[88:89], s[38:39], v10, s26, v[12:13]
	v_or_b32_e32 v10, 34, v1
	v_mad_i64_i32 v[90:91], s[38:39], v10, s26, v[12:13]
	v_or_b32_e32 v10, 35, v1
	v_mad_i64_i32 v[92:93], s[38:39], v10, s26, v[12:13]
	v_or_b32_e32 v10, 36, v1
	v_mad_i64_i32 v[94:95], s[38:39], v10, s26, v[12:13]
	v_or_b32_e32 v10, 37, v1
	v_mad_i64_i32 v[96:97], s[38:39], v10, s26, v[12:13]
	v_or_b32_e32 v10, 38, v1
	v_mad_i64_i32 v[98:99], s[38:39], v10, s26, v[12:13]
	v_or_b32_e32 v10, 39, v1
	v_mad_i64_i32 v[100:101], s[38:39], v10, s26, v[12:13]
	v_or_b32_e32 v10, 40, v1
	global_load_dword v80, v[86:87], off nt
	global_load_dword v84, v[88:89], off nt
	global_load_dword v81, v[90:91], off nt
	global_load_dword v82, v[92:93], off nt
	global_load_dword v79, v[94:95], off nt
	global_load_dword v83, v[96:97], off nt
	global_load_dword v77, v[98:99], off nt
	global_load_dword v78, v[100:101], off nt
	v_mad_i64_i32 v[94:95], s[38:39], v10, s26, v[12:13]
	v_or_b32_e32 v10, 41, v1
	v_mad_i64_i32 v[96:97], s[38:39], v10, s26, v[12:13]
	v_or_b32_e32 v10, 42, v1
	v_mad_i64_i32 v[98:99], s[38:39], v10, s26, v[12:13]
	v_or_b32_e32 v10, 43, v1
	v_mad_i64_i32 v[100:101], s[38:39], v10, s26, v[12:13]
	v_or_b32_e32 v10, 44, v1
	v_mad_i64_i32 v[102:103], s[38:39], v10, s26, v[12:13]
	v_or_b32_e32 v10, 45, v1
	v_mad_i64_i32 v[104:105], s[38:39], v10, s26, v[12:13]
	v_or_b32_e32 v10, 46, v1
	v_mad_i64_i32 v[106:107], s[38:39], v10, s26, v[12:13]
	v_or_b32_e32 v10, 47, v1
	v_mad_i64_i32 v[110:111], s[38:39], v10, s26, v[12:13]
	v_or_b32_e32 v10, 48, v1
	global_load_dword v88, v[94:95], off nt
	global_load_dword v92, v[96:97], off nt
	global_load_dword v89, v[98:99], off nt
	global_load_dword v90, v[100:101], off nt
	global_load_dword v87, v[102:103], off nt
	global_load_dword v91, v[104:105], off nt
	global_load_dword v85, v[106:107], off nt
	global_load_dword v86, v[110:111], off nt
	v_mad_i64_i32 v[102:103], s[38:39], v10, s26, v[12:13]
	v_or_b32_e32 v10, 49, v1
	v_mad_i64_i32 v[104:105], s[38:39], v10, s26, v[12:13]
	v_or_b32_e32 v10, 50, v1
	v_mad_i64_i32 v[106:107], s[38:39], v10, s26, v[12:13]
	v_or_b32_e32 v10, 51, v1
	v_mad_i64_i32 v[110:111], s[38:39], v10, s26, v[12:13]
	v_or_b32_e32 v10, 52, v1
	v_mad_i64_i32 v[112:113], s[38:39], v10, s26, v[12:13]
	v_or_b32_e32 v10, 53, v1
	v_mad_i64_i32 v[114:115], s[38:39], v10, s26, v[12:13]
	v_or_b32_e32 v10, 54, v1
	v_mad_i64_i32 v[116:117], s[38:39], v10, s26, v[12:13]
	v_or_b32_e32 v10, 55, v1
	v_mad_i64_i32 v[118:119], s[38:39], v10, s26, v[12:13]
	v_or_b32_e32 v10, 56, v1
	global_load_dword v96, v[102:103], off nt
	global_load_dword v100, v[104:105], off nt
	global_load_dword v97, v[106:107], off nt
	global_load_dword v98, v[110:111], off nt
	global_load_dword v95, v[112:113], off nt
	global_load_dword v99, v[114:115], off nt
	global_load_dword v93, v[116:117], off nt
	global_load_dword v94, v[118:119], off nt
	v_or_b32_e32 v101, 57, v1
	v_or_b32_e32 v102, 58, v1
	v_or_b32_e32 v103, 59, v1
	v_or_b32_e32 v104, 60, v1
	v_or_b32_e32 v105, 61, v1
	v_or_b32_e32 v106, 62, v1
	v_or_b32_e32 v1, 63, v1
	v_mad_i64_i32 v[110:111], s[38:39], v10, s26, v[12:13]
	v_mad_i64_i32 v[112:113], s[38:39], v101, s26, v[12:13]
	v_mad_i64_i32 v[114:115], s[38:39], v102, s26, v[12:13]
	v_mad_i64_i32 v[116:117], s[38:39], v103, s26, v[12:13]
	v_mad_i64_i32 v[118:119], s[38:39], v104, s26, v[12:13]
	v_mad_i64_i32 v[120:121], s[38:39], v105, s26, v[12:13]
	v_mad_i64_i32 v[122:123], s[38:39], v106, s26, v[12:13]
	v_mad_i64_i32 v[12:13], s[26:27], v1, s26, v[12:13]
	global_load_dword v104, v[110:111], off nt
	global_load_dword v108, v[112:113], off nt
	global_load_dword v105, v[114:115], off nt
	global_load_dword v106, v[116:117], off nt
	global_load_dword v102, v[118:119], off nt
	global_load_dword v107, v[120:121], off nt
	global_load_dword v103, v[122:123], off nt
	global_load_dword v101, v[12:13], off nt
	s_movk_i32 s26, 0x2400
	v_cmp_gt_i32_e32 vcc, s26, v0
	s_and_saveexec_b64 s[38:39], vcc
	s_cbranch_execz .LBB0_58
	s_lshl_b32 s26, s75, 8
	v_lshl_add_u32 v110, v2, 2, s26
	s_waitcnt vmcnt(63)
	v_mul_f32_e32 v111, 0xbfb8aa3b, v126
	v_exp_f32_e32 v111, v111
	s_nop 0
	v_add_f32_e32 v111, 1.0, v111
	v_div_scale_f32 v112, s[42:43], v111, v111, v126
	v_rcp_f32_e32 v113, v112
	v_div_scale_f32 v114, vcc, v126, v111, v126
	v_fma_f32 v115, -v112, v113, 1.0
	v_fmac_f32_e32 v113, v115, v113
	v_mul_f32_e32 v115, v114, v113
	v_fma_f32 v116, -v112, v115, v114
	v_fmac_f32_e32 v115, v116, v113
	v_fma_f32 v112, -v112, v115, v114
	v_div_fmas_f32 v112, v112, v113, v115
	v_div_fixup_f32 v10, v112, v111, v126
	ds_write_b32 v110, v10
	v_mul_f32_e32 v111, 0xbfb8aa3b, v127
	v_exp_f32_e32 v111, v111
	s_nop 0
	v_add_f32_e32 v111, 1.0, v111
	v_div_scale_f32 v112, s[42:43], v111, v111, v127
	v_rcp_f32_e32 v113, v112
	v_div_scale_f32 v114, vcc, v127, v111, v127
	v_fma_f32 v115, -v112, v113, 1.0
	v_fmac_f32_e32 v113, v115, v113
	v_mul_f32_e32 v115, v114, v113
	v_fma_f32 v116, -v112, v115, v114
	v_fmac_f32_e32 v115, v116, v113
	v_fma_f32 v112, -v112, v115, v114
	v_div_fmas_f32 v112, v112, v113, v115
	v_div_fixup_f32 v10, v112, v111, v127
	ds_write_b32 v110, v10 offset:2048
	v_mul_f32_e32 v111, 0xbfb8aa3b, v128
	v_exp_f32_e32 v111, v111
	s_nop 0
	v_add_f32_e32 v111, 1.0, v111
	v_div_scale_f32 v112, s[42:43], v111, v111, v128
	v_rcp_f32_e32 v113, v112
	v_div_scale_f32 v114, vcc, v128, v111, v128
	v_fma_f32 v115, -v112, v113, 1.0
	v_fmac_f32_e32 v113, v115, v113
	v_mul_f32_e32 v115, v114, v113
	v_fma_f32 v116, -v112, v115, v114
	v_fmac_f32_e32 v115, v116, v113
	v_fma_f32 v112, -v112, v115, v114
	v_div_fmas_f32 v112, v112, v113, v115
	v_div_fixup_f32 v10, v112, v111, v128
	ds_write_b32 v110, v10 offset:4096
	v_mul_f32_e32 v111, 0xbfb8aa3b, v129
	v_exp_f32_e32 v111, v111
	s_nop 0
	v_add_f32_e32 v111, 1.0, v111
	v_div_scale_f32 v112, s[42:43], v111, v111, v129
	v_rcp_f32_e32 v113, v112
	v_div_scale_f32 v114, vcc, v129, v111, v129
	v_fma_f32 v115, -v112, v113, 1.0
	v_fmac_f32_e32 v113, v115, v113
	v_mul_f32_e32 v115, v114, v113
	v_fma_f32 v116, -v112, v115, v114
	v_fmac_f32_e32 v115, v116, v113
	v_fma_f32 v112, -v112, v115, v114
	v_div_fmas_f32 v112, v112, v113, v115
	v_div_fixup_f32 v10, v112, v111, v129
	ds_write_b32 v110, v10 offset:6144
	v_mul_f32_e32 v111, 0xbfb8aa3b, v130
	v_exp_f32_e32 v111, v111
	s_nop 0
	v_add_f32_e32 v111, 1.0, v111
	v_div_scale_f32 v112, s[42:43], v111, v111, v130
	v_rcp_f32_e32 v113, v112
	v_div_scale_f32 v114, vcc, v130, v111, v130
	v_fma_f32 v115, -v112, v113, 1.0
	v_fmac_f32_e32 v113, v115, v113
	v_mul_f32_e32 v115, v114, v113
	v_fma_f32 v116, -v112, v115, v114
	v_fmac_f32_e32 v115, v116, v113
	v_fma_f32 v112, -v112, v115, v114
	v_div_fmas_f32 v112, v112, v113, v115
	v_div_fixup_f32 v10, v112, v111, v130
	ds_write_b32 v110, v10 offset:8192
	v_mul_f32_e32 v111, 0xbfb8aa3b, v131
	v_exp_f32_e32 v111, v111
	s_nop 0
	v_add_f32_e32 v111, 1.0, v111
	v_div_scale_f32 v112, s[42:43], v111, v111, v131
	v_rcp_f32_e32 v113, v112
	v_div_scale_f32 v114, vcc, v131, v111, v131
	v_fma_f32 v115, -v112, v113, 1.0
	v_fmac_f32_e32 v113, v115, v113
	v_mul_f32_e32 v115, v114, v113
	v_fma_f32 v116, -v112, v115, v114
	v_fmac_f32_e32 v115, v116, v113
	v_fma_f32 v112, -v112, v115, v114
	v_div_fmas_f32 v112, v112, v113, v115
	v_div_fixup_f32 v10, v112, v111, v131
	ds_write_b32 v110, v10 offset:10240
	v_mul_f32_e32 v111, 0xbfb8aa3b, v132
	v_exp_f32_e32 v111, v111
	s_nop 0
	v_add_f32_e32 v111, 1.0, v111
	v_div_scale_f32 v112, s[42:43], v111, v111, v132
	v_rcp_f32_e32 v113, v112
	v_div_scale_f32 v114, vcc, v132, v111, v132
	v_fma_f32 v115, -v112, v113, 1.0
	v_fmac_f32_e32 v113, v115, v113
	v_mul_f32_e32 v115, v114, v113
	v_fma_f32 v116, -v112, v115, v114
	v_fmac_f32_e32 v115, v116, v113
	v_fma_f32 v112, -v112, v115, v114
	v_div_fmas_f32 v112, v112, v113, v115
	v_div_fixup_f32 v10, v112, v111, v132
	ds_write_b32 v110, v10 offset:12288
	v_mul_f32_e32 v111, 0xbfb8aa3b, v133
	v_exp_f32_e32 v111, v111
	s_nop 0
	v_add_f32_e32 v111, 1.0, v111
	v_div_scale_f32 v112, s[42:43], v111, v111, v133
	v_rcp_f32_e32 v113, v112
	v_div_scale_f32 v114, vcc, v133, v111, v133
	v_fma_f32 v115, -v112, v113, 1.0
	v_fmac_f32_e32 v113, v115, v113
	v_mul_f32_e32 v115, v114, v113
	v_fma_f32 v116, -v112, v115, v114
	v_fmac_f32_e32 v115, v116, v113
	v_fma_f32 v112, -v112, v115, v114
	v_div_fmas_f32 v112, v112, v113, v115
	v_div_fixup_f32 v10, v112, v111, v133
	ds_write_b32 v110, v10 offset:14336
	v_mul_f32_e32 v111, 0xbfb8aa3b, v134
	v_exp_f32_e32 v111, v111
	s_nop 0
	v_add_f32_e32 v111, 1.0, v111
	v_div_scale_f32 v112, s[42:43], v111, v111, v134
	v_rcp_f32_e32 v113, v112
	v_div_scale_f32 v114, vcc, v134, v111, v134
	v_fma_f32 v115, -v112, v113, 1.0
	v_fmac_f32_e32 v113, v115, v113
	v_mul_f32_e32 v115, v114, v113
	v_fma_f32 v116, -v112, v115, v114
	v_fmac_f32_e32 v115, v116, v113
	v_fma_f32 v112, -v112, v115, v114
	v_div_fmas_f32 v112, v112, v113, v115
	v_div_fixup_f32 v10, v112, v111, v134
	ds_write_b32 v110, v10 offset:16384
	v_mul_f32_e32 v111, 0xbfb8aa3b, v135
	v_exp_f32_e32 v111, v111
	s_nop 0
	v_add_f32_e32 v111, 1.0, v111
	v_div_scale_f32 v112, s[42:43], v111, v111, v135
	v_rcp_f32_e32 v113, v112
	v_div_scale_f32 v114, vcc, v135, v111, v135
	v_fma_f32 v115, -v112, v113, 1.0
	v_fmac_f32_e32 v113, v115, v113
	v_mul_f32_e32 v115, v114, v113
	v_fma_f32 v116, -v112, v115, v114
	v_fmac_f32_e32 v115, v116, v113
	v_fma_f32 v112, -v112, v115, v114
	v_div_fmas_f32 v112, v112, v113, v115
	v_div_fixup_f32 v10, v112, v111, v135
	ds_write_b32 v110, v10 offset:18432
	v_mul_f32_e32 v111, 0xbfb8aa3b, v136
	v_exp_f32_e32 v111, v111
	s_nop 0
	v_add_f32_e32 v111, 1.0, v111
	v_div_scale_f32 v112, s[42:43], v111, v111, v136
	v_rcp_f32_e32 v113, v112
	v_div_scale_f32 v114, vcc, v136, v111, v136
	v_fma_f32 v115, -v112, v113, 1.0
	v_fmac_f32_e32 v113, v115, v113
	v_mul_f32_e32 v115, v114, v113
	v_fma_f32 v116, -v112, v115, v114
	v_fmac_f32_e32 v115, v116, v113
	v_fma_f32 v112, -v112, v115, v114
	v_div_fmas_f32 v112, v112, v113, v115
	v_div_fixup_f32 v10, v112, v111, v136
	ds_write_b32 v110, v10 offset:20480
	v_mul_f32_e32 v111, 0xbfb8aa3b, v137
	v_exp_f32_e32 v111, v111
	s_nop 0
	v_add_f32_e32 v111, 1.0, v111
	v_div_scale_f32 v112, s[42:43], v111, v111, v137
	v_rcp_f32_e32 v113, v112
	v_div_scale_f32 v114, vcc, v137, v111, v137
	v_fma_f32 v115, -v112, v113, 1.0
	v_fmac_f32_e32 v113, v115, v113
	v_mul_f32_e32 v115, v114, v113
	v_fma_f32 v116, -v112, v115, v114
	v_fmac_f32_e32 v115, v116, v113
	v_fma_f32 v112, -v112, v115, v114
	v_div_fmas_f32 v112, v112, v113, v115
	v_div_fixup_f32 v10, v112, v111, v137
	ds_write_b32 v110, v10 offset:22528
	v_mul_f32_e32 v111, 0xbfb8aa3b, v138
	v_exp_f32_e32 v111, v111
	s_nop 0
	v_add_f32_e32 v111, 1.0, v111
	v_div_scale_f32 v112, s[42:43], v111, v111, v138
	v_rcp_f32_e32 v113, v112
	v_div_scale_f32 v114, vcc, v138, v111, v138
	v_fma_f32 v115, -v112, v113, 1.0
	v_fmac_f32_e32 v113, v115, v113
	v_mul_f32_e32 v115, v114, v113
	v_fma_f32 v116, -v112, v115, v114
	v_fmac_f32_e32 v115, v116, v113
	v_fma_f32 v112, -v112, v115, v114
	v_div_fmas_f32 v112, v112, v113, v115
	v_div_fixup_f32 v10, v112, v111, v138
	ds_write_b32 v110, v10 offset:24576
	v_mul_f32_e32 v111, 0xbfb8aa3b, v139
	v_exp_f32_e32 v111, v111
	s_nop 0
	v_add_f32_e32 v111, 1.0, v111
	v_div_scale_f32 v112, s[42:43], v111, v111, v139
	v_rcp_f32_e32 v113, v112
	v_div_scale_f32 v114, vcc, v139, v111, v139
	v_fma_f32 v115, -v112, v113, 1.0
	v_fmac_f32_e32 v113, v115, v113
	v_mul_f32_e32 v115, v114, v113
	v_fma_f32 v116, -v112, v115, v114
	v_fmac_f32_e32 v115, v116, v113
	v_fma_f32 v112, -v112, v115, v114
	v_div_fmas_f32 v112, v112, v113, v115
	v_div_fixup_f32 v10, v112, v111, v139
	ds_write_b32 v110, v10 offset:26624
	v_mul_f32_e32 v111, 0xbfb8aa3b, v140
	v_exp_f32_e32 v111, v111
	s_nop 0
	v_add_f32_e32 v111, 1.0, v111
	v_div_scale_f32 v112, s[42:43], v111, v111, v140
	v_rcp_f32_e32 v113, v112
	v_div_scale_f32 v114, vcc, v140, v111, v140
	v_fma_f32 v115, -v112, v113, 1.0
	v_fmac_f32_e32 v113, v115, v113
	v_mul_f32_e32 v115, v114, v113
	v_fma_f32 v116, -v112, v115, v114
	v_fmac_f32_e32 v115, v116, v113
	v_fma_f32 v112, -v112, v115, v114
	v_div_fmas_f32 v112, v112, v113, v115
	v_div_fixup_f32 v10, v112, v111, v140
	ds_write_b32 v110, v10 offset:28672
	v_mul_f32_e32 v111, 0xbfb8aa3b, v141
	v_exp_f32_e32 v111, v111
	s_nop 0
	v_add_f32_e32 v111, 1.0, v111
	v_div_scale_f32 v112, s[42:43], v111, v111, v141
	v_rcp_f32_e32 v113, v112
	v_div_scale_f32 v114, vcc, v141, v111, v141
	v_fma_f32 v115, -v112, v113, 1.0
	v_fmac_f32_e32 v113, v115, v113
	v_mul_f32_e32 v115, v114, v113
	v_fma_f32 v116, -v112, v115, v114
	v_fmac_f32_e32 v115, v116, v113
	v_fma_f32 v112, -v112, v115, v114
	v_div_fmas_f32 v112, v112, v113, v115
	v_div_fixup_f32 v10, v112, v111, v141
	ds_write_b32 v110, v10 offset:30720
	v_mul_f32_e32 v111, 0xbfb8aa3b, v142
	v_exp_f32_e32 v111, v111
	s_nop 0
	v_add_f32_e32 v111, 1.0, v111
	v_div_scale_f32 v112, s[42:43], v111, v111, v142
	v_rcp_f32_e32 v113, v112
	v_div_scale_f32 v114, vcc, v142, v111, v142
	v_fma_f32 v115, -v112, v113, 1.0
	v_fmac_f32_e32 v113, v115, v113
	v_mul_f32_e32 v115, v114, v113
	v_fma_f32 v116, -v112, v115, v114
	v_fmac_f32_e32 v115, v116, v113
	v_fma_f32 v112, -v112, v115, v114
	v_div_fmas_f32 v112, v112, v113, v115
	v_div_fixup_f32 v10, v112, v111, v142
	ds_write_b32 v110, v10 offset:32768
	v_mul_f32_e32 v111, 0xbfb8aa3b, v143
	v_exp_f32_e32 v111, v111
	s_nop 0
	v_add_f32_e32 v111, 1.0, v111
	v_div_scale_f32 v112, s[42:43], v111, v111, v143
	v_rcp_f32_e32 v113, v112
	v_div_scale_f32 v114, vcc, v143, v111, v143
	v_fma_f32 v115, -v112, v113, 1.0
	v_fmac_f32_e32 v113, v115, v113
	v_mul_f32_e32 v115, v114, v113
	v_fma_f32 v116, -v112, v115, v114
	v_fmac_f32_e32 v115, v116, v113
	v_fma_f32 v112, -v112, v115, v114
	v_div_fmas_f32 v112, v112, v113, v115
	v_div_fixup_f32 v10, v112, v111, v143
	ds_write_b32 v110, v10 offset:34816
